# in-proj GEMM: N-tile relabelling so that workgroups with four tiles get the cheap-epilogue column groups (load balance across epilogue kinds)
# speedup vs baseline: 1.0130x; 1.0036x over previous
.LBB0_219:
	s_lshr_b32 s2, s4, 2
	s_and_b32 s3, s4, 3
	s_lshl_b32 s3, s3, 3
	s_mov_b32 s6, 0x1001000a
	s_cmp_eq_u32 s2, 1
	s_cselect_b32 s6, 0x171b0611, s6
	s_cmp_eq_u32 s2, 2
	s_cselect_b32 s6, 0xe1c1d08, s6
	s_cmp_eq_u32 s2, 3
	s_cselect_b32 s6, 0x14090203, s6
	s_cmp_eq_u32 s2, 4
	s_cselect_b32 s6, 0x40f0512, s6
	s_cmp_eq_u32 s2, 5
	s_cselect_b32 s6, 0xc160b0d, s6
	s_cmp_eq_u32 s2, 6
	s_cselect_b32 s6, 0x191a1813, s6
	s_cmp_eq_u32 s2, 7
	s_cselect_b32 s6, 0x1507, s6
	s_lshr_b32 s6, s6, s3
	s_and_b32 s4, s6, 0xff
	s_lshl_b32 s5, s5, 8
	v_add_u32_e32 v2, s5, v219
	v_ashrrev_i32_e32 v3, 31, v2
	v_lshlrev_b64 v[4:5], 11, v[2:3]
	v_and_b32_e32 v6, 0xfffe7000, v4
	v_mov_b32_e32 v7, v5
	v_lshlrev_b32_e32 v0, 6, v2
	s_lshl_b32 s6, s4, 7
	v_lshl_add_u64 v[6:7], s[44:45], 0, v[6:7]
	v_and_b32_e32 v0, 64, v0
	v_lshl_add_u64 v[2:3], v[6:7], 0, v[0:1]
	v_add_u32_e32 v6, s6, v220
	v_ashrrev_i32_e32 v7, 31, v6
	v_lshlrev_b64 v[8:9], 11, v[6:7]
	v_and_b32_e32 v10, 0xffff7000, v8
	v_mov_b32_e32 v11, v9
	v_lshlrev_b32_e32 v0, 6, v6
	v_lshl_add_u64 v[10:11], s[42:43], 0, v[10:11]
	v_and_b32_e32 v0, 64, v0
	v_mov_b32_e32 v139, v1
	v_lshl_add_u64 v[6:7], v[10:11], 0, v[0:1]
	v_readfirstlane_b32 s2, v221
	v_add_u32_e32 v0, 0x400, v221
	v_lshl_add_u64 v[2:3], v[2:3], 0, v[138:139]
	s_waitcnt vmcnt(0)
	s_mov_b32 m0, s2
	s_mov_b64 s[8:9], 0x8000
	v_readfirstlane_b32 s2, v0
	global_load_lds_dwordx4 v[2:3], off
	v_lshl_add_u64 v[10:11], v[2:3], 0, s[8:9]
	s_mov_b32 m0, s2
	s_mov_b64 s[2:3], 0x10000
	v_add_u32_e32 v0, 0x800, v221
	global_load_lds_dwordx4 v[10:11], off
	v_lshl_add_u64 v[10:11], v[2:3], 0, s[2:3]
	v_readfirstlane_b32 s2, v0
	s_mov_b32 m0, s2
	s_mov_b64 s[2:3], 0x18000
	v_add_u32_e32 v0, 0xc00, v221
	global_load_lds_dwordx4 v[10:11], off
	v_lshl_add_u64 v[10:11], v[2:3], 0, s[2:3]
	v_readfirstlane_b32 s2, v0
	v_add_u32_e32 v0, 0x4000, v130
	s_mov_b32 m0, s2
	v_readfirstlane_b32 s2, v0
	v_add_u32_e32 v0, 0x4400, v130
	v_lshl_add_u64 v[6:7], v[6:7], 0, v[138:139]
	global_load_lds_dwordx4 v[10:11], off
	s_mov_b32 m0, s2
	v_readfirstlane_b32 s2, v0
	v_add_u32_e32 v0, 0x6000, v221
	global_load_lds_dwordx4 v[6:7], off
	v_lshl_add_u64 v[10:11], v[6:7], 0, s[8:9]
	s_mov_b32 m0, s2
	s_mov_b64 s[8:9], 0x80
	v_readfirstlane_b32 s2, v0
	v_add_u32_e32 v0, 0x6400, v221
	global_load_lds_dwordx4 v[10:11], off
	v_lshl_add_u64 v[10:11], v[2:3], 0, s[8:9]
	s_mov_b32 m0, s2
	s_mov_b64 s[30:31], 0x8080
	v_readfirstlane_b32 s2, v0
	global_load_lds_dwordx4 v[10:11], off
	v_lshl_add_u64 v[10:11], v[2:3], 0, s[30:31]
	s_mov_b32 m0, s2
	s_mov_b64 s[2:3], 0x10080
	v_add_u32_e32 v0, 0x6800, v221
	global_load_lds_dwordx4 v[10:11], off
	v_lshl_add_u64 v[10:11], v[2:3], 0, s[2:3]
	v_readfirstlane_b32 s2, v0
	s_mov_b32 m0, s2
	s_mov_b64 s[2:3], 0x18080
	v_add_u32_e32 v0, 0x6c00, v221
	v_lshl_add_u64 v[2:3], v[2:3], 0, s[2:3]
	v_readfirstlane_b32 s2, v0
	v_add_u32_e32 v0, 0xa000, v130
	global_load_lds_dwordx4 v[10:11], off
	s_mov_b32 m0, s2
	v_readfirstlane_b32 s2, v0
	v_add_u32_e32 v0, 0xa400, v130
	global_load_lds_dwordx4 v[2:3], off
	v_lshl_add_u64 v[2:3], v[6:7], 0, s[8:9]
	s_mov_b32 m0, s2
	v_readfirstlane_b32 s2, v0
	global_load_lds_dwordx4 v[2:3], off
	v_lshl_add_u64 v[2:3], v[6:7], 0, s[30:31]
	s_mov_b32 m0, s2
	v_and_b32_e32 v8, 0xfffff000, v8
	global_load_lds_dwordx4 v[2:3], off
	v_and_b32_e32 v4, 0xfffff000, v4
	v_mov_b32_e32 v2, 0
	v_lshl_add_u64 v[142:143], v[134:135], 0, v[8:9]
	v_lshl_add_u64 v[144:145], v[136:137], 0, v[4:5]
	s_mov_b32 s7, 0
	s_mov_b64 s[2:3], 0
	v_mov_b32_e32 v3, v2
	v_mov_b32_e32 v4, v2
	v_mov_b32_e32 v5, v2
	v_mov_b32_e32 v6, v2
	v_mov_b32_e32 v7, v2
	v_mov_b32_e32 v8, v2
	v_mov_b32_e32 v9, v2
	v_mov_b32_e32 v10, v2
	v_mov_b32_e32 v11, v2
	v_mov_b32_e32 v12, v2
	v_mov_b32_e32 v13, v2
	v_mov_b32_e32 v14, v2
	v_mov_b32_e32 v15, v2
	v_mov_b32_e32 v16, v2
	v_mov_b32_e32 v17, v2
	v_mov_b32_e32 v18, v2
	v_mov_b32_e32 v19, v2
	v_mov_b32_e32 v20, v2
	v_mov_b32_e32 v21, v2
	v_mov_b32_e32 v22, v2
	v_mov_b32_e32 v23, v2
	v_mov_b32_e32 v24, v2
	v_mov_b32_e32 v25, v2
	v_mov_b32_e32 v26, v2
	v_mov_b32_e32 v27, v2
	v_mov_b32_e32 v28, v2
	v_mov_b32_e32 v29, v2
	v_mov_b32_e32 v30, v2
	v_mov_b32_e32 v31, v2
	v_mov_b32_e32 v32, v2
	v_mov_b32_e32 v33, v2
	v_mov_b32_e32 v34, v2
	v_mov_b32_e32 v35, v2
	v_mov_b32_e32 v36, v2
	v_mov_b32_e32 v37, v2
	v_mov_b32_e32 v38, v2
	v_mov_b32_e32 v39, v2
	v_mov_b32_e32 v40, v2
	v_mov_b32_e32 v41, v2
	v_mov_b32_e32 v42, v2
	v_mov_b32_e32 v43, v2
	v_mov_b32_e32 v44, v2
	v_mov_b32_e32 v45, v2
	v_mov_b32_e32 v46, v2
	v_mov_b32_e32 v47, v2
	v_mov_b32_e32 v48, v2
	v_mov_b32_e32 v49, v2
	s_waitcnt vmcnt(0)
	v_mov_b32_e32 v50, v2
	v_mov_b32_e32 v51, v2
	v_mov_b32_e32 v52, v2
	v_mov_b32_e32 v53, v2
	v_mov_b32_e32 v54, v2
	v_mov_b32_e32 v55, v2
	v_mov_b32_e32 v56, v2
	v_mov_b32_e32 v57, v2
	v_mov_b32_e32 v58, v2
	v_mov_b32_e32 v59, v2
	v_mov_b32_e32 v60, v2
	v_mov_b32_e32 v61, v2
	v_mov_b32_e32 v62, v2
	v_mov_b32_e32 v63, v2
	v_mov_b32_e32 v64, v2
	v_mov_b32_e32 v65, v2
	v_mov_b32_e32 v66, v2
	v_mov_b32_e32 v67, v2
	v_mov_b32_e32 v68, v2
	v_mov_b32_e32 v69, v2
	v_mov_b32_e32 v70, v2
	v_mov_b32_e32 v71, v2
	v_mov_b32_e32 v72, v2
	v_mov_b32_e32 v73, v2
	v_mov_b32_e32 v74, v2
	v_mov_b32_e32 v75, v2
	v_mov_b32_e32 v76, v2
	v_mov_b32_e32 v77, v2
	v_mov_b32_e32 v78, v2
	v_mov_b32_e32 v79, v2
	v_mov_b32_e32 v80, v2
	v_mov_b32_e32 v81, v2
	v_mov_b32_e32 v82, v2
	v_mov_b32_e32 v83, v2
	v_mov_b32_e32 v84, v2
	v_mov_b32_e32 v85, v2
	v_mov_b32_e32 v86, v2
	v_mov_b32_e32 v87, v2
	v_mov_b32_e32 v88, v2
	v_mov_b32_e32 v89, v2
	v_mov_b32_e32 v90, v2
	v_mov_b32_e32 v91, v2
	v_mov_b32_e32 v92, v2
	v_mov_b32_e32 v93, v2
	v_mov_b32_e32 v94, v2
	v_mov_b32_e32 v95, v2
	v_mov_b32_e32 v96, v2
	v_mov_b32_e32 v97, v2
	v_mov_b32_e32 v98, v2
	v_mov_b32_e32 v99, v2
	v_mov_b32_e32 v100, v2
	v_mov_b32_e32 v101, v2
	v_mov_b32_e32 v102, v2
	v_mov_b32_e32 v103, v2
	v_mov_b32_e32 v104, v2
	v_mov_b32_e32 v105, v2
	v_mov_b32_e32 v106, v2
	v_mov_b32_e32 v107, v2
	v_mov_b32_e32 v108, v2
	v_mov_b32_e32 v109, v2
	v_mov_b32_e32 v110, v2
	v_mov_b32_e32 v111, v2
	v_mov_b32_e32 v112, v2
	v_mov_b32_e32 v113, v2
	v_mov_b32_e32 v114, v2
	v_mov_b32_e32 v115, v2
	v_mov_b32_e32 v116, v2
	v_mov_b32_e32 v117, v2
	v_mov_b32_e32 v118, v2
	v_mov_b32_e32 v119, v2
	v_mov_b32_e32 v120, v2
	v_mov_b32_e32 v121, v2
	v_mov_b32_e32 v122, v2
	v_mov_b32_e32 v123, v2
	v_mov_b32_e32 v124, v2
	v_mov_b32_e32 v125, v2
	v_mov_b32_e32 v126, v2
	v_mov_b32_e32 v127, v2
	v_mov_b32_e32 v128, v2
	v_mov_b32_e32 v129, v2
